# convert loop: counted vmcnt waits per quarter (20/16/12/8) so cvt starts as each 4 loads land (lever 1)
# speedup vs baseline: 1.0005x; 1.0005x over previous
; __device__ __forceinline__ unsigned pack2bf(float lo, float hi) { unsigned r; asm("v_cvt_pk_bf16_f32 %0, %1, %2" : "=v"(r) : "v"(lo), "v"(hi)); return r; }
; __device__ void phase_convert(PP p, unsigned char* smem) {
;     ...
;       for (int j = 0; j < 8; ++j) w[j] = pack2bf(tile[(kg * 16 + 2 * j) * 129 + n], tile[(kg * 16 + 2 * j + 1) * 129 + n]);
;       bf16_t* dp = dst + (size_t)(n0 + n) * K + k0 + kg * 16;
;       *(u32x4*)dp = (u32x4){w[0], w[1], w[2], w[3]};
;       *(u32x4*)(dp + 8) = (u32x4){w[4], w[5], w[6], w[7]};
.Lcvp_loop:
	s_waitcnt vmcnt(20)
	v_cvt_pk_bf16_f32 v114, v50, v54
	v_cvt_pk_bf16_f32 v115, v58, v62
	v_cvt_pk_bf16_f32 v122, v51, v55
	v_cvt_pk_bf16_f32 v123, v59, v63
	v_cvt_pk_bf16_f32 v130, v52, v56
	v_cvt_pk_bf16_f32 v131, v60, v64
	v_cvt_pk_bf16_f32 v138, v53, v57
	v_cvt_pk_bf16_f32 v139, v61, v65
	s_waitcnt vmcnt(16)
	v_cvt_pk_bf16_f32 v116, v66, v70
	v_cvt_pk_bf16_f32 v117, v74, v78
	v_cvt_pk_bf16_f32 v124, v67, v71
	v_cvt_pk_bf16_f32 v125, v75, v79
	v_cvt_pk_bf16_f32 v132, v68, v72
	v_cvt_pk_bf16_f32 v133, v76, v80
	v_cvt_pk_bf16_f32 v140, v69, v73
	v_cvt_pk_bf16_f32 v141, v77, v81
	s_waitcnt vmcnt(12)
	v_cvt_pk_bf16_f32 v118, v82, v86
	v_cvt_pk_bf16_f32 v119, v90, v94
	v_cvt_pk_bf16_f32 v126, v83, v87
	v_cvt_pk_bf16_f32 v127, v91, v95
	v_cvt_pk_bf16_f32 v134, v84, v88
	v_cvt_pk_bf16_f32 v135, v92, v96
	v_cvt_pk_bf16_f32 v142, v85, v89
	v_cvt_pk_bf16_f32 v143, v93, v97
	s_waitcnt vmcnt(8)
	v_cvt_pk_bf16_f32 v120, v98, v102
	v_cvt_pk_bf16_f32 v121, v106, v110
	v_cvt_pk_bf16_f32 v128, v99, v103
	v_cvt_pk_bf16_f32 v129, v107, v111
	v_cvt_pk_bf16_f32 v136, v100, v104
	v_cvt_pk_bf16_f32 v137, v108, v112
	v_cvt_pk_bf16_f32 v144, v101, v105
	v_cvt_pk_bf16_f32 v145, v109, v113
	s_add_u32 s17, s98, s100
